# hand-scheduled software-pipelined dilated attention compute (5 key tiles unrolled), GEMM2 residual loads hoisted under grid barrier + nt
# speedup vs baseline: 1.1182x; 1.0635x over previous
.LBB0_361:
	v_lshrrev_b32_e32 v15, 6, v0
	v_and_b32_e32 v16, 15, v0
	v_bfe_u32 v148, v0, 4, 2
	v_readfirstlane_b32 s92, v15
	v_lshl_or_b32 v17, v15, 5, v16
	v_lshlrev_b32_e32 v146, 2, v148
	v_sub_u32_e32 v14, v16, v146
	v_mov_b32_e32 v15, 0x90
	v_mul_u32_u24_e32 v194, v17, v15
	v_lshl_add_u32 v194, v148, 4, v194
	v_add_u32_e32 v194, 16, v194
	v_lshrrev_b32_e32 v195, 2, v16
	v_add_u32_e32 v195, v195, v146
	v_lshl_add_u32 v195, s92, 5, v195
	v_mul_u32_u24_e32 v195, v195, v15
	v_and_b32_e32 v16, 3, v0
	v_lshl_add_u32 v195, v16, 3, v195
	v_add_u32_e32 v195, 0xd810, v195
	ds_read_b128 v[178:181], v194 offset:0
	ds_read_b128 v[182:185], v194 offset:64
	ds_read_b128 v[186:189], v194 offset:2304
	ds_read_b128 v[190:193], v194 offset:2368
	ds_read_b64_tr_b16 v[200:201], v195 offset:0
	ds_read_b64_tr_b16 v[202:203], v195 offset:2304
	ds_read_b64_tr_b16 v[204:205], v195 offset:32
	ds_read_b64_tr_b16 v[206:207], v195 offset:2336
	ds_read_b64_tr_b16 v[208:209], v195 offset:64
	ds_read_b64_tr_b16 v[210:211], v195 offset:2368
	ds_read_b64_tr_b16 v[212:213], v195 offset:96
	ds_read_b64_tr_b16 v[214:215], v195 offset:2400
	s_sub_i32 s93, 4, s92
	s_max_i32 s93, s93, 0
	s_cmp_eq_u32 s17, 0
	s_cselect_b32 s93, 0, s93
	v_cmp_le_i32_e64 s[76:77], v14, 0
	v_cmp_le_i32_e64 s[78:79], v14, 1
	v_cmp_le_i32_e64 s[80:81], v14, 2
	v_cmp_le_i32_e64 s[82:83], v14, 3
	v_cmp_ge_i32_e64 s[84:85], v14, 0
	v_cmp_ge_i32_e64 s[86:87], v14, 1
	v_cmp_ge_i32_e64 s[88:89], v14, 2
	v_cmp_ge_i32_e64 s[90:91], v14, 3
	v_mov_b32_e32 v10, 0x3f803f80
	v_mov_b32_e32 v11, v10
	v_mov_b32_e32 v12, v10
	v_mov_b32_e32 v13, v10
	v_mov_b32_e32 v138, 0
	v_mov_b32_e32 v139, 0
	v_mov_b32_e32 v140, 0
	v_mov_b32_e32 v141, 0
	v_mov_b32_e32 v118, 0
	v_mov_b32_e32 v119, 0
	v_mov_b32_e32 v120, 0
	v_mov_b32_e32 v121, 0
	v_mov_b32_e32 v134, 0
	v_mov_b32_e32 v135, 0
	v_mov_b32_e32 v136, 0
	v_mov_b32_e32 v137, 0
	v_mov_b32_e32 v130, 0
	v_mov_b32_e32 v131, 0
	v_mov_b32_e32 v132, 0
	v_mov_b32_e32 v133, 0
	v_mov_b32_e32 v126, 0
	v_mov_b32_e32 v127, 0
	v_mov_b32_e32 v128, 0
	v_mov_b32_e32 v129, 0
	v_mov_b32_e32 v122, 0
	v_mov_b32_e32 v123, 0
	v_mov_b32_e32 v124, 0
	v_mov_b32_e32 v125, 0
	v_mov_b32_e32 v114, 0
	v_mov_b32_e32 v115, 0
	v_mov_b32_e32 v116, 0
	v_mov_b32_e32 v117, 0
	v_mov_b32_e32 v106, 0
	v_mov_b32_e32 v107, 0
	v_mov_b32_e32 v108, 0
	v_mov_b32_e32 v109, 0
	v_mov_b32_e32 v110, 0
	v_mov_b32_e32 v111, 0
	v_mov_b32_e32 v112, 0
	v_mov_b32_e32 v113, 0
	v_mov_b32_e32 v102, 0
	v_mov_b32_e32 v103, 0
	v_mov_b32_e32 v104, 0
	v_mov_b32_e32 v105, 0
	s_waitcnt lgkmcnt(8)
	v_mfma_f32_16x16x32_bf16 v[150:153], v[178:181], v[74:77], v[66:69]
	v_mfma_f32_16x16x32_bf16 v[154:157], v[186:189], v[74:77], v[66:69]
	v_mfma_f32_16x16x32_bf16 v[162:165], v[186:189], v[82:85], v[66:69]
	v_mfma_f32_16x16x32_bf16 v[150:153], v[182:185], v[70:73], v[150:153]
	v_mfma_f32_16x16x32_bf16 v[154:157], v[190:193], v[70:73], v[154:157]
	v_mfma_f32_16x16x32_bf16 v[162:165], v[190:193], v[78:81], v[162:165]
	s_waitcnt lgkmcnt(0)
	ds_read_b128 v[178:181], v194 offset:4608
	ds_read_b128 v[182:185], v194 offset:4672
	ds_read_b128 v[186:189], v194 offset:6912
	ds_read_b128 v[190:193], v194 offset:6976
	ds_read_b64_tr_b16 v[216:217], v195 offset:4608
	ds_read_b64_tr_b16 v[218:219], v195 offset:6912
	ds_read_b64_tr_b16 v[220:221], v195 offset:4640
	ds_read_b64_tr_b16 v[222:223], v195 offset:6944
	ds_read_b64_tr_b16 v[224:225], v195 offset:4672
	ds_read_b64_tr_b16 v[226:227], v195 offset:6976
	ds_read_b64_tr_b16 v[228:229], v195 offset:4704
	ds_read_b64_tr_b16 v[230:231], v195 offset:7008
.Lattn_blk0:
	s_cmp_le_u32 s93, 0
	s_cbranch_scc0 .Lattn_min0
	s_waitcnt lgkmcnt(8)
	v_mfma_f32_16x16x32_bf16 v[166:169], v[178:181], v[74:77], v[66:69]
	v_exp_f32_e32 v150, v150
	v_mfma_f32_16x16x32_bf16 v[244:247], v[178:181], v[82:85], v[66:69]
	v_exp_f32_e32 v151, v151
	v_mfma_f32_16x16x32_bf16 v[170:173], v[186:189], v[74:77], v[66:69]
	v_exp_f32_e32 v152, v152
	v_mfma_f32_16x16x32_bf16 v[248:251], v[186:189], v[82:85], v[66:69]
	v_exp_f32_e32 v153, v153
	v_mfma_f32_16x16x32_bf16 v[166:169], v[182:185], v[70:73], v[166:169]
	v_exp_f32_e32 v154, v154
	v_mfma_f32_16x16x32_bf16 v[244:247], v[182:185], v[78:81], v[244:247]
	v_exp_f32_e32 v155, v155
	v_mfma_f32_16x16x32_bf16 v[170:173], v[190:193], v[70:73], v[170:173]
	v_exp_f32_e32 v156, v156
	v_mfma_f32_16x16x32_bf16 v[248:251], v[190:193], v[78:81], v[248:251]
	v_exp_f32_e32 v157, v157
	s_nop 0
	v_cndmask_b32_e64 v150, 0, v150, s[76:77]
	v_cndmask_b32_e64 v151, 0, v151, s[78:79]
	v_cndmask_b32_e64 v152, 0, v152, s[80:81]
	v_cndmask_b32_e64 v153, 0, v153, s[82:83]
	v_cvt_pk_bf16_f32 v2, v150, v151
	v_cvt_pk_bf16_f32 v3, v152, v153
	v_cvt_pk_bf16_f32 v4, v154, v155
	v_cvt_pk_bf16_f32 v5, v156, v157
	v_exp_f32_e32 v162, v162
	v_exp_f32_e32 v163, v163
	v_mfma_f32_16x16x32_bf16 v[138:141], v[10:13], v[2:5], v[138:141]
	v_exp_f32_e32 v164, v164
	v_exp_f32_e32 v165, v165
	v_mfma_f32_16x16x32_bf16 v[134:137], v[200:203], v[2:5], v[134:137]
	v_mfma_f32_16x16x32_bf16 v[130:133], v[204:207], v[2:5], v[130:133]
	v_mfma_f32_16x16x32_bf16 v[126:129], v[208:211], v[2:5], v[126:129]
	v_mfma_f32_16x16x32_bf16 v[122:125], v[212:215], v[2:5], v[122:125]
	s_nop 0
	v_mov_b32_e32 v6, 0
	v_mov_b32_e32 v7, 0
	v_cndmask_b32_e64 v162, 0, v162, s[76:77]
	v_cndmask_b32_e64 v163, 0, v163, s[78:79]
	v_cndmask_b32_e64 v164, 0, v164, s[80:81]
	v_cndmask_b32_e64 v165, 0, v165, s[82:83]
	v_cvt_pk_bf16_f32 v8, v162, v163
	v_cvt_pk_bf16_f32 v9, v164, v165
	s_waitcnt lgkmcnt(0)
	s_nop 1
	v_mfma_f32_16x16x32_bf16 v[118:121], v[10:13], v[6:9], v[118:121]
	ds_read_b128 v[178:181], v194 offset:9216
	v_mfma_f32_16x16x32_bf16 v[114:117], v[200:203], v[6:9], v[114:117]
	ds_read_b128 v[182:185], v194 offset:9280
	v_mfma_f32_16x16x32_bf16 v[106:109], v[204:207], v[6:9], v[106:109]
	ds_read_b128 v[186:189], v194 offset:11520
	v_mfma_f32_16x16x32_bf16 v[110:113], v[208:211], v[6:9], v[110:113]
	ds_read_b128 v[190:193], v194 offset:11584
	v_mfma_f32_16x16x32_bf16 v[102:105], v[212:215], v[6:9], v[102:105]
	ds_read_b64_tr_b16 v[200:201], v195 offset:9216
	ds_read_b64_tr_b16 v[202:203], v195 offset:11520
	ds_read_b64_tr_b16 v[204:205], v195 offset:9248
	ds_read_b64_tr_b16 v[206:207], v195 offset:11552
	ds_read_b64_tr_b16 v[208:209], v195 offset:9280
	ds_read_b64_tr_b16 v[210:211], v195 offset:11584
	ds_read_b64_tr_b16 v[212:213], v195 offset:9312
	ds_read_b64_tr_b16 v[214:215], v195 offset:11616
	s_branch .Lattn_end0
.Lattn_min0:
	s_waitcnt lgkmcnt(8)
	v_mfma_f32_16x16x32_bf16 v[166:169], v[178:181], v[74:77], v[66:69]
	v_mfma_f32_16x16x32_bf16 v[244:247], v[178:181], v[82:85], v[66:69]
	v_mfma_f32_16x16x32_bf16 v[170:173], v[186:189], v[74:77], v[66:69]
	v_mfma_f32_16x16x32_bf16 v[248:251], v[186:189], v[82:85], v[66:69]
	v_mfma_f32_16x16x32_bf16 v[166:169], v[182:185], v[70:73], v[166:169]
	v_mfma_f32_16x16x32_bf16 v[244:247], v[182:185], v[78:81], v[244:247]
	v_mfma_f32_16x16x32_bf16 v[170:173], v[190:193], v[70:73], v[170:173]
	v_mfma_f32_16x16x32_bf16 v[248:251], v[190:193], v[78:81], v[248:251]
	s_waitcnt lgkmcnt(0)
	ds_read_b128 v[178:181], v194 offset:9216
	ds_read_b128 v[182:185], v194 offset:9280
	ds_read_b128 v[186:189], v194 offset:11520
	ds_read_b128 v[190:193], v194 offset:11584
	ds_read_b64_tr_b16 v[200:201], v195 offset:9216
	ds_read_b64_tr_b16 v[202:203], v195 offset:11520
	ds_read_b64_tr_b16 v[204:205], v195 offset:9248
	ds_read_b64_tr_b16 v[206:207], v195 offset:11552
	ds_read_b64_tr_b16 v[208:209], v195 offset:9280
	ds_read_b64_tr_b16 v[210:211], v195 offset:11584
	ds_read_b64_tr_b16 v[212:213], v195 offset:9312
	ds_read_b64_tr_b16 v[214:215], v195 offset:11616
.Lattn_end0:
.Lattn_blk1:
	s_cmp_le_u32 s93, 1
	s_cbranch_scc0 .Lattn_min1
	s_waitcnt lgkmcnt(8)
	v_mfma_f32_16x16x32_bf16 v[150:153], v[178:181], v[74:77], v[66:69]
	v_exp_f32_e32 v166, v166
	v_mfma_f32_16x16x32_bf16 v[158:161], v[178:181], v[82:85], v[66:69]
	v_exp_f32_e32 v167, v167
	v_mfma_f32_16x16x32_bf16 v[154:157], v[186:189], v[74:77], v[66:69]
	v_exp_f32_e32 v168, v168
	v_mfma_f32_16x16x32_bf16 v[162:165], v[186:189], v[82:85], v[66:69]
	v_exp_f32_e32 v169, v169
	v_mfma_f32_16x16x32_bf16 v[150:153], v[182:185], v[70:73], v[150:153]
	v_exp_f32_e32 v170, v170
	v_mfma_f32_16x16x32_bf16 v[158:161], v[182:185], v[78:81], v[158:161]
	v_exp_f32_e32 v171, v171
	v_mfma_f32_16x16x32_bf16 v[154:157], v[190:193], v[70:73], v[154:157]
	v_exp_f32_e32 v172, v172
	v_mfma_f32_16x16x32_bf16 v[162:165], v[190:193], v[78:81], v[162:165]
	v_exp_f32_e32 v173, v173
	s_nop 0
	v_cvt_pk_bf16_f32 v2, v166, v167
	v_cvt_pk_bf16_f32 v3, v168, v169
	v_cvt_pk_bf16_f32 v4, v170, v171
	v_cvt_pk_bf16_f32 v5, v172, v173
	v_exp_f32_e32 v244, v244
	v_exp_f32_e32 v245, v245
	v_mfma_f32_16x16x32_bf16 v[138:141], v[10:13], v[2:5], v[138:141]
	v_exp_f32_e32 v246, v246
	v_exp_f32_e32 v247, v247
	v_mfma_f32_16x16x32_bf16 v[134:137], v[216:219], v[2:5], v[134:137]
	v_exp_f32_e32 v248, v248
	v_exp_f32_e32 v249, v249
	v_mfma_f32_16x16x32_bf16 v[130:133], v[220:223], v[2:5], v[130:133]
	v_exp_f32_e32 v250, v250
	v_exp_f32_e32 v251, v251
	v_mfma_f32_16x16x32_bf16 v[126:129], v[224:227], v[2:5], v[126:129]
	v_mfma_f32_16x16x32_bf16 v[122:125], v[228:231], v[2:5], v[122:125]
	s_nop 0
	v_cvt_pk_bf16_f32 v6, v244, v245
	v_cvt_pk_bf16_f32 v7, v246, v247
	v_cvt_pk_bf16_f32 v8, v248, v249
	v_cvt_pk_bf16_f32 v9, v250, v251
	s_waitcnt lgkmcnt(0)
	s_nop 1
	v_mfma_f32_16x16x32_bf16 v[118:121], v[10:13], v[6:9], v[118:121]
	ds_read_b128 v[178:181], v194 offset:13824
	v_mfma_f32_16x16x32_bf16 v[114:117], v[216:219], v[6:9], v[114:117]
	ds_read_b128 v[182:185], v194 offset:13888
	v_mfma_f32_16x16x32_bf16 v[106:109], v[220:223], v[6:9], v[106:109]
	ds_read_b128 v[186:189], v194 offset:16128
	v_mfma_f32_16x16x32_bf16 v[110:113], v[224:227], v[6:9], v[110:113]
	ds_read_b128 v[190:193], v194 offset:16192
	v_mfma_f32_16x16x32_bf16 v[102:105], v[228:231], v[6:9], v[102:105]
	ds_read_b64_tr_b16 v[216:217], v195 offset:13824
	ds_read_b64_tr_b16 v[218:219], v195 offset:16128
	ds_read_b64_tr_b16 v[220:221], v195 offset:13856
	ds_read_b64_tr_b16 v[222:223], v195 offset:16160
	ds_read_b64_tr_b16 v[224:225], v195 offset:13888
	ds_read_b64_tr_b16 v[226:227], v195 offset:16192
	ds_read_b64_tr_b16 v[228:229], v195 offset:13920
	ds_read_b64_tr_b16 v[230:231], v195 offset:16224
	s_branch .Lattn_end1
.Lattn_min1:
	s_waitcnt lgkmcnt(8)
	v_mfma_f32_16x16x32_bf16 v[150:153], v[178:181], v[74:77], v[66:69]
	v_mfma_f32_16x16x32_bf16 v[158:161], v[178:181], v[82:85], v[66:69]
	v_mfma_f32_16x16x32_bf16 v[154:157], v[186:189], v[74:77], v[66:69]
	v_mfma_f32_16x16x32_bf16 v[162:165], v[186:189], v[82:85], v[66:69]
	v_mfma_f32_16x16x32_bf16 v[150:153], v[182:185], v[70:73], v[150:153]
	v_mfma_f32_16x16x32_bf16 v[158:161], v[182:185], v[78:81], v[158:161]
	v_mfma_f32_16x16x32_bf16 v[154:157], v[190:193], v[70:73], v[154:157]
	v_mfma_f32_16x16x32_bf16 v[162:165], v[190:193], v[78:81], v[162:165]
	s_waitcnt lgkmcnt(0)
	ds_read_b128 v[178:181], v194 offset:13824
	ds_read_b128 v[182:185], v194 offset:13888
	ds_read_b128 v[186:189], v194 offset:16128
	ds_read_b128 v[190:193], v194 offset:16192
	ds_read_b64_tr_b16 v[216:217], v195 offset:13824
	ds_read_b64_tr_b16 v[218:219], v195 offset:16128
	ds_read_b64_tr_b16 v[220:221], v195 offset:13856
	ds_read_b64_tr_b16 v[222:223], v195 offset:16160
	ds_read_b64_tr_b16 v[224:225], v195 offset:13888
	ds_read_b64_tr_b16 v[226:227], v195 offset:16192
	ds_read_b64_tr_b16 v[228:229], v195 offset:13920
	ds_read_b64_tr_b16 v[230:231], v195 offset:16224
.Lattn_end1:
.Lattn_blk2:
	s_cmp_le_u32 s93, 2
	s_cbranch_scc0 .Lattn_min2
	s_waitcnt lgkmcnt(8)
	v_mfma_f32_16x16x32_bf16 v[166:169], v[178:181], v[74:77], v[66:69]
	v_exp_f32_e32 v150, v150
	v_mfma_f32_16x16x32_bf16 v[244:247], v[178:181], v[82:85], v[66:69]
	v_exp_f32_e32 v151, v151
	v_mfma_f32_16x16x32_bf16 v[170:173], v[186:189], v[74:77], v[66:69]
	v_exp_f32_e32 v152, v152
	v_mfma_f32_16x16x32_bf16 v[248:251], v[186:189], v[82:85], v[66:69]
	v_exp_f32_e32 v153, v153
	v_mfma_f32_16x16x32_bf16 v[166:169], v[182:185], v[70:73], v[166:169]
	v_exp_f32_e32 v154, v154
	v_mfma_f32_16x16x32_bf16 v[244:247], v[182:185], v[78:81], v[244:247]
	v_exp_f32_e32 v155, v155
	v_mfma_f32_16x16x32_bf16 v[170:173], v[190:193], v[70:73], v[170:173]
	v_exp_f32_e32 v156, v156
	v_mfma_f32_16x16x32_bf16 v[248:251], v[190:193], v[78:81], v[248:251]
	v_exp_f32_e32 v157, v157
	s_nop 0
	v_cvt_pk_bf16_f32 v2, v150, v151
	v_cvt_pk_bf16_f32 v3, v152, v153
	v_cvt_pk_bf16_f32 v4, v154, v155
	v_cvt_pk_bf16_f32 v5, v156, v157
	v_exp_f32_e32 v158, v158
	v_exp_f32_e32 v159, v159
	v_mfma_f32_16x16x32_bf16 v[138:141], v[10:13], v[2:5], v[138:141]
	v_exp_f32_e32 v160, v160
	v_exp_f32_e32 v161, v161
	v_mfma_f32_16x16x32_bf16 v[134:137], v[200:203], v[2:5], v[134:137]
	v_exp_f32_e32 v162, v162
	v_exp_f32_e32 v163, v163
	v_mfma_f32_16x16x32_bf16 v[130:133], v[204:207], v[2:5], v[130:133]
	v_exp_f32_e32 v164, v164
	v_exp_f32_e32 v165, v165
	v_mfma_f32_16x16x32_bf16 v[126:129], v[208:211], v[2:5], v[126:129]
	v_mfma_f32_16x16x32_bf16 v[122:125], v[212:215], v[2:5], v[122:125]
	s_nop 0
	v_cvt_pk_bf16_f32 v6, v158, v159
	v_cvt_pk_bf16_f32 v7, v160, v161
	v_cvt_pk_bf16_f32 v8, v162, v163
	v_cvt_pk_bf16_f32 v9, v164, v165
	s_waitcnt lgkmcnt(0)
	s_nop 1
	v_mfma_f32_16x16x32_bf16 v[118:121], v[10:13], v[6:9], v[118:121]
	ds_read_b128 v[178:181], v194 offset:18432
	v_mfma_f32_16x16x32_bf16 v[114:117], v[200:203], v[6:9], v[114:117]
	ds_read_b128 v[182:185], v194 offset:18496
	v_mfma_f32_16x16x32_bf16 v[106:109], v[204:207], v[6:9], v[106:109]
	ds_read_b128 v[186:189], v194 offset:20736
	v_mfma_f32_16x16x32_bf16 v[110:113], v[208:211], v[6:9], v[110:113]
	ds_read_b128 v[190:193], v194 offset:20800
	v_mfma_f32_16x16x32_bf16 v[102:105], v[212:215], v[6:9], v[102:105]
	ds_read_b64_tr_b16 v[200:201], v195 offset:18432
	ds_read_b64_tr_b16 v[202:203], v195 offset:20736
	ds_read_b64_tr_b16 v[204:205], v195 offset:18464
	ds_read_b64_tr_b16 v[206:207], v195 offset:20768
	ds_read_b64_tr_b16 v[208:209], v195 offset:18496
	ds_read_b64_tr_b16 v[210:211], v195 offset:20800
	ds_read_b64_tr_b16 v[212:213], v195 offset:18528
	ds_read_b64_tr_b16 v[214:215], v195 offset:20832
	s_branch .Lattn_end2
.Lattn_min2:
	s_waitcnt lgkmcnt(8)
	v_mfma_f32_16x16x32_bf16 v[166:169], v[178:181], v[74:77], v[66:69]
	v_mfma_f32_16x16x32_bf16 v[244:247], v[178:181], v[82:85], v[66:69]
	v_mfma_f32_16x16x32_bf16 v[170:173], v[186:189], v[74:77], v[66:69]
	v_mfma_f32_16x16x32_bf16 v[248:251], v[186:189], v[82:85], v[66:69]
	v_mfma_f32_16x16x32_bf16 v[166:169], v[182:185], v[70:73], v[166:169]
	v_mfma_f32_16x16x32_bf16 v[244:247], v[182:185], v[78:81], v[244:247]
	v_mfma_f32_16x16x32_bf16 v[170:173], v[190:193], v[70:73], v[170:173]
	v_mfma_f32_16x16x32_bf16 v[248:251], v[190:193], v[78:81], v[248:251]
	s_waitcnt lgkmcnt(0)
	ds_read_b128 v[178:181], v194 offset:18432
	ds_read_b128 v[182:185], v194 offset:18496
	ds_read_b128 v[186:189], v194 offset:20736
	ds_read_b128 v[190:193], v194 offset:20800
	ds_read_b64_tr_b16 v[200:201], v195 offset:18432
	ds_read_b64_tr_b16 v[202:203], v195 offset:20736
	ds_read_b64_tr_b16 v[204:205], v195 offset:18464
	ds_read_b64_tr_b16 v[206:207], v195 offset:20768
	ds_read_b64_tr_b16 v[208:209], v195 offset:18496
	ds_read_b64_tr_b16 v[210:211], v195 offset:20800
	ds_read_b64_tr_b16 v[212:213], v195 offset:18528
	ds_read_b64_tr_b16 v[214:215], v195 offset:20832
.Lattn_end2:
.Lattn_blk3:
	s_cmp_le_u32 s93, 3
	s_cbranch_scc0 .Lattn_min3
	s_waitcnt lgkmcnt(8)
	v_mfma_f32_16x16x32_bf16 v[150:153], v[178:181], v[74:77], v[66:69]
	v_exp_f32_e32 v166, v166
	v_mfma_f32_16x16x32_bf16 v[158:161], v[178:181], v[82:85], v[66:69]
	v_exp_f32_e32 v167, v167
	v_mfma_f32_16x16x32_bf16 v[162:165], v[186:189], v[82:85], v[66:69]
	v_exp_f32_e32 v168, v168
	v_mfma_f32_16x16x32_bf16 v[150:153], v[182:185], v[70:73], v[150:153]
	v_exp_f32_e32 v169, v169
	v_mfma_f32_16x16x32_bf16 v[158:161], v[182:185], v[78:81], v[158:161]
	v_exp_f32_e32 v170, v170
	v_mfma_f32_16x16x32_bf16 v[162:165], v[190:193], v[78:81], v[162:165]
	v_exp_f32_e32 v171, v171
	v_exp_f32_e32 v172, v172
	v_exp_f32_e32 v173, v173
	s_nop 0
	v_cvt_pk_bf16_f32 v2, v166, v167
	v_cvt_pk_bf16_f32 v3, v168, v169
	v_cvt_pk_bf16_f32 v4, v170, v171
	v_cvt_pk_bf16_f32 v5, v172, v173
	v_exp_f32_e32 v244, v244
	v_exp_f32_e32 v245, v245
	v_mfma_f32_16x16x32_bf16 v[138:141], v[10:13], v[2:5], v[138:141]
	v_exp_f32_e32 v246, v246
	v_exp_f32_e32 v247, v247
	v_mfma_f32_16x16x32_bf16 v[134:137], v[216:219], v[2:5], v[134:137]
	v_exp_f32_e32 v248, v248
	v_exp_f32_e32 v249, v249
	v_mfma_f32_16x16x32_bf16 v[130:133], v[220:223], v[2:5], v[130:133]
	v_exp_f32_e32 v250, v250
	v_exp_f32_e32 v251, v251
	v_mfma_f32_16x16x32_bf16 v[126:129], v[224:227], v[2:5], v[126:129]
	v_mfma_f32_16x16x32_bf16 v[122:125], v[228:231], v[2:5], v[122:125]
	s_nop 0
	v_cvt_pk_bf16_f32 v6, v244, v245
	v_cvt_pk_bf16_f32 v7, v246, v247
	v_cvt_pk_bf16_f32 v8, v248, v249
	v_cvt_pk_bf16_f32 v9, v250, v251
	s_nop 1
	v_mfma_f32_16x16x32_bf16 v[118:121], v[10:13], v[6:9], v[118:121]
	v_mfma_f32_16x16x32_bf16 v[114:117], v[216:219], v[6:9], v[114:117]
	v_mfma_f32_16x16x32_bf16 v[106:109], v[220:223], v[6:9], v[106:109]
	v_mfma_f32_16x16x32_bf16 v[110:113], v[224:227], v[6:9], v[110:113]
	v_mfma_f32_16x16x32_bf16 v[102:105], v[228:231], v[6:9], v[102:105]
	s_branch .Lattn_end3
.Lattn_min3:
	s_waitcnt lgkmcnt(8)
	v_mfma_f32_16x16x32_bf16 v[150:153], v[178:181], v[74:77], v[66:69]
	v_mfma_f32_16x16x32_bf16 v[158:161], v[178:181], v[82:85], v[66:69]
	v_mfma_f32_16x16x32_bf16 v[162:165], v[186:189], v[82:85], v[66:69]
	v_mfma_f32_16x16x32_bf16 v[150:153], v[182:185], v[70:73], v[150:153]
	v_mfma_f32_16x16x32_bf16 v[158:161], v[182:185], v[78:81], v[158:161]
	v_mfma_f32_16x16x32_bf16 v[162:165], v[190:193], v[78:81], v[162:165]
.Lattn_end3:
.Lattn_blk4:
	s_cmp_le_u32 s93, 4
	s_cbranch_scc0 .Lattn_min4
	s_nop 7
	v_exp_f32_e32 v150, v150
	v_exp_f32_e32 v151, v151
	v_exp_f32_e32 v152, v152
	v_exp_f32_e32 v153, v153
	s_nop 0
	v_cndmask_b32_e64 v150, 0, v150, s[84:85]
	v_cndmask_b32_e64 v151, 0, v151, s[86:87]
	v_cndmask_b32_e64 v152, 0, v152, s[88:89]
	v_cndmask_b32_e64 v153, 0, v153, s[90:91]
	v_cvt_pk_bf16_f32 v2, v150, v151
	v_cvt_pk_bf16_f32 v3, v152, v153
	v_mov_b32_e32 v4, 0
	v_mov_b32_e32 v5, 0
	v_exp_f32_e32 v158, v158
	v_exp_f32_e32 v159, v159
	s_waitcnt lgkmcnt(0)
	v_mfma_f32_16x16x32_bf16 v[138:141], v[10:13], v[2:5], v[138:141]
	v_exp_f32_e32 v160, v160
	v_exp_f32_e32 v161, v161
	v_mfma_f32_16x16x32_bf16 v[134:137], v[200:203], v[2:5], v[134:137]
	v_exp_f32_e32 v162, v162
	v_exp_f32_e32 v163, v163
	v_mfma_f32_16x16x32_bf16 v[130:133], v[204:207], v[2:5], v[130:133]
	v_exp_f32_e32 v164, v164
	v_exp_f32_e32 v165, v165
	v_mfma_f32_16x16x32_bf16 v[126:129], v[208:211], v[2:5], v[126:129]
	v_mfma_f32_16x16x32_bf16 v[122:125], v[212:215], v[2:5], v[122:125]
	s_nop 0
	v_cvt_pk_bf16_f32 v6, v158, v159
	v_cvt_pk_bf16_f32 v7, v160, v161
	v_cndmask_b32_e64 v162, 0, v162, s[84:85]
	v_cndmask_b32_e64 v163, 0, v163, s[86:87]
	v_cndmask_b32_e64 v164, 0, v164, s[88:89]
	v_cndmask_b32_e64 v165, 0, v165, s[90:91]
	v_cvt_pk_bf16_f32 v8, v162, v163
	v_cvt_pk_bf16_f32 v9, v164, v165
	s_nop 1
	v_mfma_f32_16x16x32_bf16 v[118:121], v[10:13], v[6:9], v[118:121]
	v_mfma_f32_16x16x32_bf16 v[114:117], v[200:203], v[6:9], v[114:117]
	v_mfma_f32_16x16x32_bf16 v[106:109], v[204:207], v[6:9], v[106:109]
	v_mfma_f32_16x16x32_bf16 v[110:113], v[208:211], v[6:9], v[110:113]
	v_mfma_f32_16x16x32_bf16 v[102:105], v[212:215], v[6:9], v[102:105]
	s_branch .Lattn_end4

.Lattn_end4:
	s_ashr_i32 s19, s18, 31
	s_lshl_b64 s[6:7], s[18:19], 14
	s_add_u32 s18, s6, s20
	s_addc_u32 s19, s7, s21
	s_lshl_b64 s[6:7], s[18:19], 5
	s_add_u32 s9, s24, s6
	s_mov_b32 s17, s15
	s_addc_u32 s10, s25, s7
	s_lshl_b64 s[6:7], s[16:17], 2
	s_add_u32 s6, s9, s6
	s_addc_u32 s7, s10, s7
	s_lshl_b64 s[10:11], s[14:15], 3
	v_cmp_eq_u32_e32 vcc, 0, v148
	v_ashrrev_i32_e32 v1, 31, v17
	s_and_saveexec_b64 s[20:21], vcc
	s_cbranch_execz .LBB0_373
	v_mul_lo_u32 v4, s11, v17
	v_mul_lo_u32 v5, s10, v1
	v_mad_u64_u32 v[2:3], s[34:35], s10, v17, 0
	v_add3_u32 v3, v3, v5, v4
	v_lshl_add_u64 v[2:3], v[2:3], 2, s[6:7]
	global_store_dword v[2:3], v138, off

.LBB0_522:
	s_or_b64 exec, exec, s[4:5]
	s_mov_b32 s90, 0
	s_cmpk_lg_u32 s33, 0x100
	s_cbranch_scc1 .Lg2_nopre
	s_load_dwordx2 s[74:75], s[0:1], 0x0
	s_and_b32 s76, s2, 7
	s_lshl_b32 s76, s76, 3
	s_bfe_u32 s77, s2, 0x30003
	s_add_u32 s76, s76, s77
	s_lshr_b32 s77, s2, 6
	s_lshl_b32 s76, s76, 8
	s_lshl_b32 s77, s77, 8
	v_lshrrev_b32_e32 v244, 8, v0
	v_and_b32_e32 v245, 15, v0
	v_lshl_or_b32 v244, v244, 6, v245
	v_add_u32_e32 v244, s76, v244
	v_bfe_u32 v245, v0, 6, 2
	v_bfe_u32 v246, v0, 4, 2
	v_lshlrev_b32_e32 v245, 5, v245
	v_lshl_or_b32 v245, v246, 3, v245
	v_add_u32_e32 v245, s77, v245
	v_lshlrev_b32_e32 v245, 2, v245
	v_lshl_add_u32 v157, v244, 12, v245
	s_waitcnt lgkmcnt(0)
	s_add_u32 s76, s74, 0x10000
	s_addc_u32 s77, s75, 0
	s_add_u32 s78, s74, 0x20000
	s_addc_u32 s79, s75, 0
	s_add_u32 s80, s74, 0x30000
	s_addc_u32 s81, s75, 0
	s_add_u32 s82, s74, 0x80000
	s_addc_u32 s83, s75, 0
	s_add_u32 s84, s74, 0x90000
	s_addc_u32 s85, s75, 0
	s_add_u32 s86, s74, 0xa0000
	s_addc_u32 s87, s75, 0
	s_add_u32 s88, s74, 0xb0000
	s_addc_u32 s89, s75, 0
	global_load_dwordx4 v[10:13], v157, s[74:75] offset:16 nt
	global_load_dwordx4 v[14:17], v157, s[74:75] nt
	global_load_dwordx4 v[2:5], v157, s[74:75] offset:528 nt
	global_load_dwordx4 v[6:9], v157, s[74:75] offset:512 nt
	global_load_dwordx4 v[26:29], v157, s[76:77] offset:16 nt
	global_load_dwordx4 v[30:33], v157, s[76:77] nt
	global_load_dwordx4 v[18:21], v157, s[76:77] offset:528 nt
	global_load_dwordx4 v[22:25], v157, s[76:77] offset:512 nt
	global_load_dwordx4 v[54:57], v157, s[78:79] offset:16 nt
	global_load_dwordx4 v[62:65], v157, s[78:79] nt
	global_load_dwordx4 v[34:37], v157, s[78:79] offset:528 nt
	global_load_dwordx4 v[38:41], v157, s[78:79] offset:512 nt
	global_load_dwordx4 v[86:89], v157, s[80:81] offset:16 nt
	global_load_dwordx4 v[94:97], v157, s[80:81] nt
	global_load_dwordx4 v[66:69], v157, s[80:81] offset:528 nt
	global_load_dwordx4 v[70:73], v157, s[80:81] offset:512 nt
	global_load_dwordx4 v[50:53], v157, s[82:83] offset:16 nt
	global_load_dwordx4 v[58:61], v157, s[82:83] nt
	global_load_dwordx4 v[42:45], v157, s[82:83] offset:528 nt
	global_load_dwordx4 v[46:49], v157, s[82:83] offset:512 nt
	global_load_dwordx4 v[82:85], v157, s[84:85] offset:16 nt
	global_load_dwordx4 v[90:93], v157, s[84:85] nt
	global_load_dwordx4 v[74:77], v157, s[84:85] offset:528 nt
	global_load_dwordx4 v[78:81], v157, s[84:85] offset:512 nt
	global_load_dwordx4 v[106:109], v157, s[86:87] offset:16 nt
	global_load_dwordx4 v[110:113], v157, s[86:87] nt
	global_load_dwordx4 v[98:101], v157, s[86:87] offset:528 nt
	global_load_dwordx4 v[102:105], v157, s[86:87] offset:512 nt
	global_load_dwordx4 v[122:125], v157, s[88:89] offset:16 nt
	global_load_dwordx4 v[126:129], v157, s[88:89] nt
	global_load_dwordx4 v[114:117], v157, s[88:89] offset:528 nt
	global_load_dwordx4 v[118:121], v157, s[88:89] offset:512 nt
	s_mov_b32 s90, 1
.Lg2_nopre:
	s_andn2_b64 vcc, exec, s[12:13]
	s_waitcnt lgkmcnt(0)
	s_barrier
	s_cbranch_vccnz .LBB0_531
	s_load_dwordx2 s[4:5], s[0:1], 0x70
	s_load_dwordx2 s[6:7], s[0:1], 0xc0
	s_load_dwordx2 s[8:9], s[0:1], 0x80
	s_load_dwordx2 s[10:11], s[0:1], 0x0
	v_bitop3_b32 v246, v238, v241, 48 bitop3:0x6c
	v_and_or_b32 v248, v242, 4, v239
	v_and_b32_e32 v254, 24, v243
	v_or_b32_e32 v247, v246, v235
	v_or_b32_e32 v244, v248, v254
	v_and_or_b32 v245, v240, 48, v236
	v_and_b32_e32 v249, 32, v240
	v_lshl_or_b32 v130, v245, 11, v247
	v_or_b32_e32 v245, v244, v249
	v_or_b32_e32 v250, 0x2000, v238
	v_lshl_or_b32 v132, v245, 11, v247
	v_lshrrev_b32_e32 v245, 7, v250
	s_movk_i32 s0, 0x70
	v_and_or_b32 v251, v245, s0, v236
	s_waitcnt lgkmcnt(0)
	s_add_u32 s0, s10, 0x10000
	s_addc_u32 s1, s11, 0
	s_add_u32 s12, s10, 0x20000
	s_addc_u32 s13, s11, 0
	s_add_u32 s14, s10, 0x30000
	s_addc_u32 s15, s11, 0
	s_add_u32 s16, s10, 0x80000
	s_addc_u32 s17, s11, 0
	s_add_u32 s18, s10, 0x90000
	s_addc_u32 s19, s11, 0
	s_add_u32 s20, s10, 0xa0000
	s_addc_u32 s21, s11, 0
	s_add_u32 s22, s10, 0xb0000
	v_lshl_or_b32 v134, v251, 11, v247
	v_and_b32_e32 v251, 0x60, v245
	s_addc_u32 s23, s11, 0
	v_or_b32_e32 v244, v244, v251
	s_add_u32 s24, s4, 0x10000
	v_lshl_or_b32 v136, v244, 11, v247
	v_lshlrev_b32_e32 v252, 1, v254
	v_and_b32_e32 v244, 0x3c0, v237
	v_and_b32_e32 v245, 32, v234
	s_addc_u32 s25, s5, 0
	v_bitop3_b32 v154, v252, v245, v244 bitop3:0x36
	s_add_u32 s26, s4, 0x20000
	v_lshlrev_b32_e32 v244, 8, v0
	s_mov_b32 s3, 0x18000
	v_mov_b32_e32 v133, 0
	s_addc_u32 s27, s5, 0
	v_and_or_b32 v244, v244, s3, v246
	s_add_u32 s28, s4, 0x30000
	v_or3_b32 v244, v244, v199, v235
	v_mov_b32_e32 v245, v133
	s_addc_u32 s29, s5, 0
	v_lshl_add_u64 v[138:139], s[6:7], 0, v[244:245]
	v_lshlrev_b32_e32 v244, 4, v250
	s_mov_b32 s3, 0x38000
	s_add_u32 s30, s4, 0x80000
	v_and_or_b32 v244, v244, s3, v246
	s_addc_u32 s31, s5, 0
	v_or3_b32 v244, v244, v199, v235
	s_add_u32 s34, s4, 0x90000
	v_lshl_add_u64 v[140:141], s[6:7], 0, v[244:245]
	v_or3_b32 v244, v249, v254, v248
	s_addc_u32 s35, s5, 0
	v_lshl_or_b32 v244, v244, 11, v247
	s_add_u32 s36, s4, 0xa0000
	v_lshl_add_u64 v[142:143], s[8:9], 0, v[244:245]
	v_or3_b32 v244, v251, v254, v248
	s_addc_u32 s37, s5, 0
	v_lshl_or_b32 v244, v244, 11, v247
	s_add_u32 s38, s4, 0xb0000
	v_lshl_add_u64 v[144:145], s[8:9], 0, v[244:245]
	v_lshlrev_b32_e32 v244, 2, v197
	v_mov_b32_e32 v137, v133
	v_mov_b32_e32 v131, v133
	v_mov_b32_e32 v135, v133
	s_addc_u32 s39, s5, 0
	v_lshl_or_b32 v155, v197, 6, v252
	v_and_b32_e32 v156, 32, v244
	s_mov_b64 s[40:41], 0x80
	s_mov_b64 s[42:43], 0x40080
	s_mov_b64 s[44:45], 0x100
	s_mov_b64 s[46:47], 0x40100
	s_mov_b64 s[48:49], 0x180
	s_mov_b64 s[50:51], 0x40180
	s_branch .LBB0_525

.LBB0_525:
	s_ashr_i32 s3, s2, 31
	s_lshr_b32 s3, s3, 29
	s_add_i32 s3, s2, s3
	s_ashr_i32 s52, s3, 3
	s_and_b32 s3, s3, -8
	s_sub_i32 s3, s2, s3
	s_lshr_b32 s53, s3, 31
	s_or_b32 s53, s53, 32
	s_mul_i32 s67, s53, s3
	s_add_i32 s67, s67, s52
	s_ashr_i32 s3, s67, 31
	s_lshr_b32 s3, s3, 27
	s_add_i32 s3, s67, s3
	s_ashr_i32 s68, s3, 5
	s_lshl_b32 s54, s68, 3
	s_sub_i32 s52, 64, s54
	s_min_u32 s55, s52, 8
	s_andn2_b32 s3, s3, 31
	s_sub_i32 s3, s67, s3
	v_cvt_f32_ubyte0_e32 v245, s55
	v_cvt_f32_i32_e32 v244, s3
	v_rcp_iflag_f32_e32 v246, v245
	s_ashr_i32 s52, s3, 30
	s_or_b32 s56, s52, 1
	s_cmp_eq_u32 s90, 1
	s_cbranch_scc1 .Lg2_nowait
	s_waitcnt vmcnt(0)
.Lg2_nowait:
	v_mul_f32_e32 v246, v244, v246
	v_trunc_f32_e32 v246, v246
	v_fma_f32 v244, -v246, v245, v244
	v_cvt_i32_f32_e32 v246, v246
	v_cmp_ge_f32_e64 s[52:53], |v244|, v245
	s_and_b64 s[52:53], s[52:53], exec
	s_cselect_b32 s52, s56, 0
	v_readfirstlane_b32 s53, v246
	s_add_i32 s69, s53, s52
	s_sext_i32_i8 s52, s69
	s_mul_i32 s69, s69, s55
	s_sub_i32 s3, s3, s69
	s_sext_i32_i8 s3, s3
	s_add_i32 s54, s54, s3
	s_lshl_b32 s56, s54, 8
	s_lshl_b32 s58, s52, 8
	v_readfirstlane_b32 s3, v0
	s_lshr_b32 s66, s3, 6
	s_ashr_i32 s57, s56, 31
	s_ashr_i32 s59, s58, 31
	s_lshr_b32 s65, s3, 8
	s_lshl_b32 s62, s66, 10
	s_lshl_b64 s[52:53], s[56:57], 11
	s_lshl_b64 s[54:55], s[58:59], 11
	s_add_u32 s60, s8, s54
	s_addc_u32 s61, s9, s55
	s_add_i32 s57, s62, 16
	s_add_i32 m0, s57, 0x10000
	v_lshl_add_u64 v[244:245], s[60:61], 0, v[132:133]
	global_load_lds_dwordx4 v[244:245], off
	s_add_i32 m0, s57, 0x12000
	s_add_u32 s52, s6, s52
	v_lshl_add_u64 v[246:247], s[60:61], 0, v[136:137]
	s_addc_u32 s53, s7, s53
	s_add_i32 s59, s57, 0x2000
	global_load_lds_dwordx4 v[246:247], off
	v_lshl_add_u64 v[250:251], s[52:53], 0, v[130:131]
	s_mov_b32 m0, s57
	s_add_u32 s70, s60, 0x40000
	global_load_lds_dwordx4 v[250:251], off
	v_lshl_add_u64 v[248:249], s[52:53], 0, v[134:135]
	s_mov_b32 m0, s59
	s_addc_u32 s71, s61, 0
	global_load_lds_dwordx4 v[248:249], off
	s_add_i32 m0, s57, 0x14000
	v_lshl_add_u64 v[252:253], s[70:71], 0, v[132:133]
	global_load_lds_dwordx4 v[252:253], off
	s_add_i32 m0, s57, 0x16000
	v_lshl_add_u64 v[252:253], s[70:71], 0, v[136:137]
	s_add_u32 s70, s52, 0x40000
	s_addc_u32 s71, s53, 0
	s_add_i32 s63, s57, 0x4000
	global_load_lds_dwordx4 v[252:253], off
	v_lshl_add_u64 v[252:253], s[70:71], 0, v[130:131]
	s_mov_b32 m0, s63
	s_add_i32 s64, s57, 0x6000
	global_load_lds_dwordx4 v[252:253], off
	v_lshl_add_u64 v[252:253], s[70:71], 0, v[134:135]
	s_mov_b32 m0, s64
	s_cmp_lg_u32 s65, 1
	global_load_lds_dwordx4 v[252:253], off
	s_cbranch_scc1 .LBB0_527
	s_barrier
.LBB0_527:
	s_lshl_b32 s66, s66, 5
	s_add_i32 m0, s57, 0x18000
	v_lshl_add_u64 v[244:245], v[244:245], 0, s[40:41]
	v_lshl_or_b32 v252, s65, 6, v197
	s_lshl_b32 s70, s65, 13
	s_and_b32 s71, s66, 0x60
	s_waitcnt vmcnt(4)
	s_barrier
	global_load_lds_dwordx4 v[244:245], off
	v_lshl_add_u64 v[244:245], v[246:247], 0, s[40:41]
	s_add_i32 m0, s57, 0x1a000
	s_add_i32 s65, s57, 0x8000
	s_add_i32 s66, s57, 0xa000
	global_load_lds_dwordx4 v[244:245], off
	v_lshl_add_u64 v[244:245], v[250:251], 0, s[40:41]
	s_mov_b32 m0, s65
	s_add_u32 s60, s60, 0x40080
	global_load_lds_dwordx4 v[244:245], off
	v_lshl_add_u64 v[244:245], v[248:249], 0, s[40:41]
	s_mov_b32 m0, s66
	s_addc_u32 s61, s61, 0
	global_load_lds_dwordx4 v[244:245], off
	s_add_i32 m0, s57, 0x1c000
	v_lshl_add_u64 v[244:245], s[60:61], 0, v[132:133]
	global_load_lds_dwordx4 v[244:245], off
	v_lshl_add_u64 v[244:245], s[60:61], 0, v[136:137]
	s_add_i32 m0, s57, 0x1e000
	s_lshl_b32 s60, s68, 5
	global_load_lds_dwordx4 v[244:245], off
	v_or_b32_e32 v245, s58, v254
	v_or_b32_e32 v245, s71, v245
	v_add_u32_e32 v244, s56, v252
	v_lshlrev_b32_e32 v245, 2, v245
	v_lshl_add_u32 v157, v244, 12, v245
	s_waitcnt vmcnt(6)
	s_barrier
	s_cmp_eq_u32 s90, 1
	s_mov_b32 s90, 0
	s_cbranch_scc1 .Lg2_skipx
	global_load_dwordx4 v[10:13], v157, s[10:11] offset:16 nt
	global_load_dwordx4 v[14:17], v157, s[10:11] nt
	global_load_dwordx4 v[2:5], v157, s[10:11] offset:528 nt
	global_load_dwordx4 v[6:9], v157, s[10:11] offset:512 nt
	global_load_dwordx4 v[26:29], v157, s[0:1] offset:16 nt
	global_load_dwordx4 v[30:33], v157, s[0:1] nt
	global_load_dwordx4 v[18:21], v157, s[0:1] offset:528 nt
	global_load_dwordx4 v[22:25], v157, s[0:1] offset:512 nt
	global_load_dwordx4 v[54:57], v157, s[12:13] offset:16 nt
	global_load_dwordx4 v[62:65], v157, s[12:13] nt
	global_load_dwordx4 v[34:37], v157, s[12:13] offset:528 nt
	global_load_dwordx4 v[38:41], v157, s[12:13] offset:512 nt
	global_load_dwordx4 v[86:89], v157, s[14:15] offset:16 nt
	global_load_dwordx4 v[94:97], v157, s[14:15] nt
	global_load_dwordx4 v[66:69], v157, s[14:15] offset:528 nt
	global_load_dwordx4 v[70:73], v157, s[14:15] offset:512 nt
	global_load_dwordx4 v[50:53], v157, s[16:17] offset:16 nt
	global_load_dwordx4 v[58:61], v157, s[16:17] nt
	global_load_dwordx4 v[42:45], v157, s[16:17] offset:528 nt
	global_load_dwordx4 v[46:49], v157, s[16:17] offset:512 nt
	global_load_dwordx4 v[82:85], v157, s[18:19] offset:16 nt
	global_load_dwordx4 v[90:93], v157, s[18:19] nt
	global_load_dwordx4 v[74:77], v157, s[18:19] offset:528 nt
	global_load_dwordx4 v[78:81], v157, s[18:19] offset:512 nt
	global_load_dwordx4 v[106:109], v157, s[20:21] offset:16 nt
	global_load_dwordx4 v[110:113], v157, s[20:21] nt
	global_load_dwordx4 v[98:101], v157, s[20:21] offset:528 nt
	global_load_dwordx4 v[102:105], v157, s[20:21] offset:512 nt
	global_load_dwordx4 v[122:125], v157, s[22:23] offset:16 nt
	global_load_dwordx4 v[126:129], v157, s[22:23] nt
	global_load_dwordx4 v[114:117], v157, s[22:23] offset:528 nt
	global_load_dwordx4 v[118:121], v157, s[22:23] offset:512 nt
.Lg2_skipx:
	s_sub_i32 s58, s67, s69
	s_sub_i32 s58, s58, s60
	s_sext_i32_i8 s58, s58
	s_lshl_b32 s56, s68, 11
	s_lshl_b32 s58, s58, 8
	s_add_i32 s60, s56, s58
	s_ashr_i32 s61, s60, 31
	v_bitop3_b32 v158, v155, s70, v156 bitop3:0xde
	s_lshl_b64 s[60:61], s[60:61], 11
	v_lshl_or_b32 v159, s71, 7, v154
	v_lshl_add_u64 v[146:147], v[138:139], 0, s[60:61]
	v_lshl_add_u64 v[148:149], v[140:141], 0, s[60:61]
	v_lshl_add_u64 v[150:151], v[142:143], 0, s[54:55]
	v_lshl_add_u64 v[152:153], v[144:145], 0, s[54:55]
	s_mov_b32 s56, -2
	s_mov_b64 s[54:55], 0
	v_add_u32_e32 v158, 16, v158
	s_waitcnt vmcnt(0)
